# sample-group GEMM (4-item variant) K-chunk loops: all 16 fragment loads issued before the first MFMA, one counted vmcnt ladder
# speedup vs baseline: 1.0113x; 1.0054x over previous
.LBB0_660:
	s_lshl_b64 s[10:11], s[10:11], 1
	v_lshl_add_u64 v[92:93], v[70:71], 0, s[10:11]
	v_add_co_u32_e32 v116, vcc, s16, v92
	v_lshl_add_u64 v[96:97], v[72:73], 0, s[10:11]
	s_nop 0
	v_addc_co_u32_e32 v117, vcc, 0, v93, vcc
	v_add_co_u32_e32 v124, vcc, s17, v92
	global_load_dwordx4 v[88:91], v[96:97], off
	s_nop 0
	v_addc_co_u32_e32 v125, vcc, 0, v93, vcc
	v_add_co_u32_e32 v134, vcc, s18, v92
	global_load_dwordx4 v[84:87], v[92:93], off
	s_nop 0
	v_addc_co_u32_e32 v135, vcc, 0, v93, vcc
	v_add_co_u32_e32 v138, vcc, s16, v96
	s_mov_b64 s[10:11], 64
	s_nop 0
	v_addc_co_u32_e32 v139, vcc, 0, v97, vcc
	v_add_co_u32_e32 v140, vcc, s17, v96
	s_nop 1
	v_addc_co_u32_e32 v141, vcc, 0, v97, vcc
	v_add_co_u32_e32 v142, vcc, s18, v96
	s_nop 1
	v_addc_co_u32_e32 v143, vcc, 0, v97, vcc
	global_load_dwordx4 v[92:95], v[92:93], off offset:64
	s_nop 0
	global_load_dwordx4 v[96:99], v[96:97], off offset:64
	s_nop 0
	global_load_dwordx4 v[100:103], v[116:117], off
	global_load_dwordx4 v[104:107], v[124:125], off
	global_load_dwordx4 v[108:111], v[134:135], off
	global_load_dwordx4 v[112:115], v[138:139], off
	s_nop 0
	global_load_dwordx4 v[116:119], v[116:117], off offset:64
	global_load_dwordx4 v[120:123], v[140:141], off
	s_nop 0
	global_load_dwordx4 v[124:127], v[124:125], off offset:64
	s_nop 0
	global_load_dwordx4 v[130:133], v[142:143], off
	s_nop 0
	global_load_dwordx4 v[134:137], v[134:135], off offset:64
	s_andn2_b64 vcc, exec, s[8:9]
	global_load_dwordx4 v[142:145], v[142:143], off offset:64
	s_mov_b64 s[8:9], 0
	global_load_dwordx4 v[160:163], v[138:139], off offset:64
	s_nop 0
	global_load_dwordx4 v[138:141], v[140:141], off offset:64
	s_waitcnt vmcnt(14)
	v_mfma_f32_16x16x32_bf16 v[8:11], v[88:91], v[84:87], v[8:11]
	s_waitcnt vmcnt(11)
	v_mfma_f32_16x16x32_bf16 v[24:27], v[88:91], v[100:103], v[24:27]
	s_waitcnt vmcnt(10)
	v_mfma_f32_16x16x32_bf16 v[36:39], v[88:91], v[104:107], v[36:39]
	s_waitcnt vmcnt(9)
	v_mfma_f32_16x16x32_bf16 v[48:51], v[88:91], v[108:111], v[48:51]
	s_waitcnt vmcnt(8)
	v_mfma_f32_16x16x32_bf16 v[0:3], v[112:115], v[84:87], v[0:3]
	s_waitcnt vmcnt(6)
	v_mfma_f32_16x16x32_bf16 v[4:7], v[120:123], v[84:87], v[4:7]
	s_waitcnt vmcnt(4)
	v_mfma_f32_16x16x32_bf16 v[12:15], v[130:133], v[84:87], v[12:15]
	v_mfma_f32_16x16x32_bf16 v[16:19], v[112:115], v[100:103], v[16:19]
	v_mfma_f32_16x16x32_bf16 v[20:23], v[120:123], v[100:103], v[20:23]
	v_mfma_f32_16x16x32_bf16 v[28:31], v[130:133], v[100:103], v[28:31]
	v_mfma_f32_16x16x32_bf16 v[32:35], v[112:115], v[104:107], v[32:35]
	v_mfma_f32_16x16x32_bf16 v[40:43], v[120:123], v[104:107], v[40:43]
	v_mfma_f32_16x16x32_bf16 v[44:47], v[130:133], v[104:107], v[44:47]
	v_mfma_f32_16x16x32_bf16 v[52:55], v[112:115], v[108:111], v[52:55]
	v_mfma_f32_16x16x32_bf16 v[56:59], v[120:123], v[108:111], v[56:59]
	v_mfma_f32_16x16x32_bf16 v[60:63], v[130:133], v[108:111], v[60:63]
	v_mfma_f32_16x16x32_bf16 v[8:11], v[96:99], v[92:95], v[8:11]
	v_mfma_f32_16x16x32_bf16 v[24:27], v[96:99], v[116:119], v[24:27]
	v_mfma_f32_16x16x32_bf16 v[36:39], v[96:99], v[124:127], v[36:39]
	s_waitcnt vmcnt(3)
	v_mfma_f32_16x16x32_bf16 v[48:51], v[96:99], v[134:137], v[48:51]
	s_waitcnt vmcnt(1)
	v_mfma_f32_16x16x32_bf16 v[0:3], v[160:163], v[92:95], v[0:3]
	s_waitcnt vmcnt(0)
	v_mfma_f32_16x16x32_bf16 v[4:7], v[138:141], v[92:95], v[4:7]
	v_mfma_f32_16x16x32_bf16 v[12:15], v[142:145], v[92:95], v[12:15]
	v_mfma_f32_16x16x32_bf16 v[16:19], v[160:163], v[116:119], v[16:19]
	v_mfma_f32_16x16x32_bf16 v[20:23], v[138:141], v[116:119], v[20:23]
	v_mfma_f32_16x16x32_bf16 v[28:31], v[142:145], v[116:119], v[28:31]
	v_mfma_f32_16x16x32_bf16 v[32:35], v[160:163], v[124:127], v[32:35]
	v_mfma_f32_16x16x32_bf16 v[40:43], v[138:141], v[124:127], v[40:43]
	v_mfma_f32_16x16x32_bf16 v[44:47], v[142:145], v[124:127], v[44:47]
	v_mfma_f32_16x16x32_bf16 v[52:55], v[160:163], v[134:137], v[52:55]
	v_mfma_f32_16x16x32_bf16 v[56:59], v[138:141], v[134:137], v[56:59]
	v_mfma_f32_16x16x32_bf16 v[60:63], v[142:145], v[134:137], v[60:63]
	s_cbranch_vccz .LBB0_660
	s_lshl_b32 s8, s12, 12
	s_and_b32 s8, s8, 0x1c0000
	s_and_b32 s9, s14, 0xfc0
	s_or_b32 s8, s9, s8
	v_add_lshl_u32 v64, s8, v76, 1
	v_lshl_add_u64 v[70:71], s[46:47], 0, v[64:65]
	s_barrier
	ds_write_b128 v80, v[8:11]
	ds_write_b128 v81, v[0:3]
	ds_write_b128 v82, v[4:7]
	ds_write_b128 v83, v[12:15]
	ds_write_b128 v80, v[24:27] offset:4096
	ds_write_b128 v81, v[16:19] offset:4096
	ds_write_b128 v82, v[20:23] offset:4096
	ds_write_b128 v83, v[28:31] offset:4096
	ds_write_b128 v80, v[36:39] offset:8192
	ds_write_b128 v81, v[32:35] offset:8192
	ds_write_b128 v82, v[40:43] offset:8192
	ds_write_b128 v83, v[44:47] offset:8192
	ds_write_b128 v80, v[48:51] offset:12288
	ds_write_b128 v81, v[52:55] offset:12288
	ds_write_b128 v82, v[56:59] offset:12288
	ds_write_b128 v83, v[60:63] offset:12288
	s_mov_b64 s[8:9], 0
	v_mov_b32_e32 v0, v78
	v_mov_b32_e32 v1, v77
	v_mov_b32_e32 v2, v75
	s_waitcnt lgkmcnt(0)
	s_barrier

.LBB0_710:
	s_lshl_b64 s[10:11], s[10:11], 1
	v_lshl_add_u64 v[92:93], v[70:71], 0, s[10:11]
	v_add_co_u32_e32 v116, vcc, s16, v92
	v_lshl_add_u64 v[96:97], v[72:73], 0, s[10:11]
	s_nop 0
	v_addc_co_u32_e32 v117, vcc, 0, v93, vcc
	v_add_co_u32_e32 v124, vcc, s17, v92
	global_load_dwordx4 v[88:91], v[96:97], off
	s_nop 0
	v_addc_co_u32_e32 v125, vcc, 0, v93, vcc
	v_add_co_u32_e32 v134, vcc, s18, v92
	global_load_dwordx4 v[84:87], v[92:93], off
	s_nop 0
	v_addc_co_u32_e32 v135, vcc, 0, v93, vcc
	v_add_co_u32_e32 v138, vcc, s16, v96
	s_mov_b64 s[10:11], 64
	s_nop 0
	v_addc_co_u32_e32 v139, vcc, 0, v97, vcc
	v_add_co_u32_e32 v140, vcc, s17, v96
	s_nop 1
	v_addc_co_u32_e32 v141, vcc, 0, v97, vcc
	v_add_co_u32_e32 v142, vcc, s18, v96
	s_nop 1
	v_addc_co_u32_e32 v143, vcc, 0, v97, vcc
	global_load_dwordx4 v[92:95], v[92:93], off offset:64
	s_nop 0
	global_load_dwordx4 v[96:99], v[96:97], off offset:64
	s_nop 0
	global_load_dwordx4 v[100:103], v[116:117], off
	global_load_dwordx4 v[104:107], v[124:125], off
	global_load_dwordx4 v[108:111], v[134:135], off
	global_load_dwordx4 v[112:115], v[138:139], off
	s_nop 0
	global_load_dwordx4 v[116:119], v[116:117], off offset:64
	global_load_dwordx4 v[120:123], v[140:141], off
	s_nop 0
	global_load_dwordx4 v[124:127], v[124:125], off offset:64
	s_nop 0
	global_load_dwordx4 v[130:133], v[142:143], off
	s_nop 0
	global_load_dwordx4 v[134:137], v[134:135], off offset:64
	s_andn2_b64 vcc, exec, s[8:9]
	global_load_dwordx4 v[142:145], v[142:143], off offset:64
	s_mov_b64 s[8:9], 0
	global_load_dwordx4 v[160:163], v[138:139], off offset:64
	s_nop 0
	global_load_dwordx4 v[138:141], v[140:141], off offset:64
	s_waitcnt vmcnt(14)
	v_mfma_f32_16x16x32_bf16 v[8:11], v[88:91], v[84:87], v[8:11]
	s_waitcnt vmcnt(11)
	v_mfma_f32_16x16x32_bf16 v[24:27], v[88:91], v[100:103], v[24:27]
	s_waitcnt vmcnt(10)
	v_mfma_f32_16x16x32_bf16 v[36:39], v[88:91], v[104:107], v[36:39]
	s_waitcnt vmcnt(9)
	v_mfma_f32_16x16x32_bf16 v[48:51], v[88:91], v[108:111], v[48:51]
	s_waitcnt vmcnt(8)
	v_mfma_f32_16x16x32_bf16 v[0:3], v[112:115], v[84:87], v[0:3]
	s_waitcnt vmcnt(6)
	v_mfma_f32_16x16x32_bf16 v[4:7], v[120:123], v[84:87], v[4:7]
	s_waitcnt vmcnt(4)
	v_mfma_f32_16x16x32_bf16 v[12:15], v[130:133], v[84:87], v[12:15]
	v_mfma_f32_16x16x32_bf16 v[16:19], v[112:115], v[100:103], v[16:19]
	v_mfma_f32_16x16x32_bf16 v[20:23], v[120:123], v[100:103], v[20:23]
	v_mfma_f32_16x16x32_bf16 v[28:31], v[130:133], v[100:103], v[28:31]
	v_mfma_f32_16x16x32_bf16 v[32:35], v[112:115], v[104:107], v[32:35]
	v_mfma_f32_16x16x32_bf16 v[40:43], v[120:123], v[104:107], v[40:43]
	v_mfma_f32_16x16x32_bf16 v[44:47], v[130:133], v[104:107], v[44:47]
	v_mfma_f32_16x16x32_bf16 v[52:55], v[112:115], v[108:111], v[52:55]
	v_mfma_f32_16x16x32_bf16 v[56:59], v[120:123], v[108:111], v[56:59]
	v_mfma_f32_16x16x32_bf16 v[60:63], v[130:133], v[108:111], v[60:63]
	v_mfma_f32_16x16x32_bf16 v[8:11], v[96:99], v[92:95], v[8:11]
	v_mfma_f32_16x16x32_bf16 v[24:27], v[96:99], v[116:119], v[24:27]
	v_mfma_f32_16x16x32_bf16 v[36:39], v[96:99], v[124:127], v[36:39]
	s_waitcnt vmcnt(3)
	v_mfma_f32_16x16x32_bf16 v[48:51], v[96:99], v[134:137], v[48:51]
	s_waitcnt vmcnt(1)
	v_mfma_f32_16x16x32_bf16 v[0:3], v[160:163], v[92:95], v[0:3]
	s_waitcnt vmcnt(0)
	v_mfma_f32_16x16x32_bf16 v[4:7], v[138:141], v[92:95], v[4:7]
	v_mfma_f32_16x16x32_bf16 v[12:15], v[142:145], v[92:95], v[12:15]
	v_mfma_f32_16x16x32_bf16 v[16:19], v[160:163], v[116:119], v[16:19]
	v_mfma_f32_16x16x32_bf16 v[20:23], v[138:141], v[116:119], v[20:23]
	v_mfma_f32_16x16x32_bf16 v[28:31], v[142:145], v[116:119], v[28:31]
	v_mfma_f32_16x16x32_bf16 v[32:35], v[160:163], v[124:127], v[32:35]
	v_mfma_f32_16x16x32_bf16 v[40:43], v[138:141], v[124:127], v[40:43]
	v_mfma_f32_16x16x32_bf16 v[44:47], v[142:145], v[124:127], v[44:47]
	v_mfma_f32_16x16x32_bf16 v[52:55], v[160:163], v[134:137], v[52:55]
	v_mfma_f32_16x16x32_bf16 v[56:59], v[138:141], v[134:137], v[56:59]
	v_mfma_f32_16x16x32_bf16 v[60:63], v[142:145], v[134:137], v[60:63]
	s_cbranch_vccz .LBB0_710
	s_lshl_b32 s8, s12, 12
	s_and_b32 s8, s8, 0x1c0000
	s_and_b32 s9, s14, 0xfc0
	s_or_b32 s8, s9, s8
	v_add_lshl_u32 v64, s8, v76, 1
	v_lshl_add_u64 v[70:71], s[46:47], 0, v[64:65]
	s_waitcnt lgkmcnt(0)
	s_barrier
	ds_write_b128 v80, v[8:11]
	ds_write_b128 v81, v[0:3]
	ds_write_b128 v82, v[4:7]
	ds_write_b128 v83, v[12:15]
	ds_write_b128 v80, v[24:27] offset:4096
	ds_write_b128 v81, v[16:19] offset:4096
	ds_write_b128 v82, v[20:23] offset:4096
	ds_write_b128 v83, v[28:31] offset:4096
	ds_write_b128 v80, v[36:39] offset:8192
	ds_write_b128 v81, v[32:35] offset:8192
	ds_write_b128 v82, v[40:43] offset:8192
	ds_write_b128 v83, v[44:47] offset:8192
	ds_write_b128 v80, v[48:51] offset:12288
	ds_write_b128 v81, v[52:55] offset:12288
	ds_write_b128 v82, v[56:59] offset:12288
	ds_write_b128 v83, v[60:63] offset:12288
	s_mov_b64 s[8:9], 0
	v_mov_b32_e32 v0, v78
	v_mov_b32_e32 v1, v77
	v_mov_b32_e32 v2, v75
	s_waitcnt lgkmcnt(0)
	s_barrier

.LBB0_1097:
	s_lshl_b64 s[8:9], s[8:9], 1
	v_lshl_add_u64 v[104:105], v[72:73], 0, s[8:9]
	v_add_co_u32_e32 v130, vcc, s12, v104
	v_lshl_add_u64 v[108:109], v[74:75], 0, s[8:9]
	s_nop 0
	v_addc_co_u32_e32 v131, vcc, 0, v105, vcc
	v_add_co_u32_e32 v138, vcc, s10, v104
	global_load_dwordx4 v[100:103], v[108:109], off
	s_nop 0
	v_addc_co_u32_e32 v139, vcc, 0, v105, vcc
	v_add_co_u32_e32 v148, vcc, s11, v104
	global_load_dwordx4 v[96:99], v[104:105], off
	s_nop 0
	v_addc_co_u32_e32 v149, vcc, 0, v105, vcc
	v_add_co_u32_e32 v152, vcc, s12, v108
	s_mov_b64 s[8:9], 64
	s_nop 0
	v_addc_co_u32_e32 v153, vcc, 0, v109, vcc
	v_add_co_u32_e32 v154, vcc, s10, v108
	s_nop 1
	v_addc_co_u32_e32 v155, vcc, 0, v109, vcc
	v_add_co_u32_e32 v156, vcc, s11, v108
	s_nop 1
	v_addc_co_u32_e32 v157, vcc, 0, v109, vcc
	global_load_dwordx4 v[104:107], v[104:105], off offset:64
	s_nop 0
	global_load_dwordx4 v[108:111], v[108:109], off offset:64
	s_nop 0
	global_load_dwordx4 v[112:115], v[130:131], off
	global_load_dwordx4 v[116:119], v[138:139], off
	global_load_dwordx4 v[120:123], v[148:149], off
	global_load_dwordx4 v[124:127], v[152:153], off
	s_nop 0
	global_load_dwordx4 v[130:133], v[130:131], off offset:64
	global_load_dwordx4 v[134:137], v[154:155], off
	s_nop 0
	global_load_dwordx4 v[138:141], v[138:139], off offset:64
	s_nop 0
	global_load_dwordx4 v[142:145], v[156:157], off
	s_nop 0
	global_load_dwordx4 v[148:151], v[148:149], off offset:64
	s_andn2_b64 vcc, exec, s[6:7]
	global_load_dwordx4 v[156:159], v[156:157], off offset:64
	s_mov_b64 s[6:7], 0
	global_load_dwordx4 v[160:163], v[152:153], off offset:64
	s_nop 0
	global_load_dwordx4 v[152:155], v[154:155], off offset:64
	s_waitcnt vmcnt(14)
	v_mfma_f32_16x16x32_bf16 v[8:11], v[100:103], v[96:99], v[8:11]
	s_waitcnt vmcnt(11)
	v_mfma_f32_16x16x32_bf16 v[24:27], v[100:103], v[112:115], v[24:27]
	s_waitcnt vmcnt(10)
	v_mfma_f32_16x16x32_bf16 v[36:39], v[100:103], v[116:119], v[36:39]
	s_waitcnt vmcnt(9)
	v_mfma_f32_16x16x32_bf16 v[48:51], v[100:103], v[120:123], v[48:51]
	s_waitcnt vmcnt(8)
	v_mfma_f32_16x16x32_bf16 v[0:3], v[124:127], v[96:99], v[0:3]
	s_waitcnt vmcnt(6)
	v_mfma_f32_16x16x32_bf16 v[4:7], v[134:137], v[96:99], v[4:7]
	s_waitcnt vmcnt(4)
	v_mfma_f32_16x16x32_bf16 v[12:15], v[142:145], v[96:99], v[12:15]
	v_mfma_f32_16x16x32_bf16 v[16:19], v[124:127], v[112:115], v[16:19]
	v_mfma_f32_16x16x32_bf16 v[20:23], v[134:137], v[112:115], v[20:23]
	v_mfma_f32_16x16x32_bf16 v[28:31], v[142:145], v[112:115], v[28:31]
	v_mfma_f32_16x16x32_bf16 v[32:35], v[124:127], v[116:119], v[32:35]
	v_mfma_f32_16x16x32_bf16 v[40:43], v[134:137], v[116:119], v[40:43]
	v_mfma_f32_16x16x32_bf16 v[44:47], v[142:145], v[116:119], v[44:47]
	v_mfma_f32_16x16x32_bf16 v[52:55], v[124:127], v[120:123], v[52:55]
	v_mfma_f32_16x16x32_bf16 v[56:59], v[134:137], v[120:123], v[56:59]
	v_mfma_f32_16x16x32_bf16 v[60:63], v[142:145], v[120:123], v[60:63]
	v_mfma_f32_16x16x32_bf16 v[8:11], v[108:111], v[104:107], v[8:11]
	v_mfma_f32_16x16x32_bf16 v[24:27], v[108:111], v[130:133], v[24:27]
	v_mfma_f32_16x16x32_bf16 v[36:39], v[108:111], v[138:141], v[36:39]
	s_waitcnt vmcnt(3)
	v_mfma_f32_16x16x32_bf16 v[48:51], v[108:111], v[148:151], v[48:51]
	s_waitcnt vmcnt(1)
	v_mfma_f32_16x16x32_bf16 v[0:3], v[160:163], v[104:107], v[0:3]
	s_waitcnt vmcnt(0)
	v_mfma_f32_16x16x32_bf16 v[4:7], v[152:155], v[104:107], v[4:7]
	v_mfma_f32_16x16x32_bf16 v[12:15], v[156:159], v[104:107], v[12:15]
	v_mfma_f32_16x16x32_bf16 v[16:19], v[160:163], v[130:133], v[16:19]
	v_mfma_f32_16x16x32_bf16 v[20:23], v[152:155], v[130:133], v[20:23]
	v_mfma_f32_16x16x32_bf16 v[28:31], v[156:159], v[130:133], v[28:31]
	v_mfma_f32_16x16x32_bf16 v[32:35], v[160:163], v[138:141], v[32:35]
	v_mfma_f32_16x16x32_bf16 v[40:43], v[152:155], v[138:141], v[40:43]
	v_mfma_f32_16x16x32_bf16 v[44:47], v[156:159], v[138:141], v[44:47]
	v_mfma_f32_16x16x32_bf16 v[52:55], v[160:163], v[148:151], v[52:55]
	v_mfma_f32_16x16x32_bf16 v[56:59], v[152:155], v[148:151], v[56:59]
	v_mfma_f32_16x16x32_bf16 v[60:63], v[156:159], v[148:151], v[60:63]
	s_cbranch_vccz .LBB0_1097
	s_waitcnt lgkmcnt(0)
	s_barrier
	ds_write_b128 v91, v[8:11]
	ds_write_b128 v92, v[0:3]
	ds_write_b128 v93, v[4:7]
	ds_write_b128 v94, v[12:15]
	ds_write_b128 v91, v[24:27] offset:4096
	ds_write_b128 v92, v[16:19] offset:4096
	ds_write_b128 v93, v[20:23] offset:4096
	ds_write_b128 v94, v[28:31] offset:4096
	ds_write_b128 v91, v[36:39] offset:8192
	ds_write_b128 v92, v[32:35] offset:8192
	ds_write_b128 v93, v[40:43] offset:8192
	ds_write_b128 v94, v[44:47] offset:8192
	ds_write_b128 v91, v[48:51] offset:12288
	ds_write_b128 v92, v[52:55] offset:12288
	ds_write_b128 v93, v[56:59] offset:12288
	ds_write_b128 v94, v[60:63] offset:12288
	s_waitcnt lgkmcnt(0)
	s_barrier
	s_and_saveexec_b64 s[6:7], s[4:5]
	s_cbranch_execz .LBB0_1095
	ds_read_b128 v[0:3], v80
	ds_read_b128 v[4:7], v81
	ds_read_b128 v[8:11], v80 offset:16384
	ds_read_b128 v[12:15], v81 offset:16384
	v_mov_b32_e32 v71, v65
	s_waitcnt lgkmcnt(3)
	v_pk_add_f32 v[2:3], v[2:3], 0 op_sel_hi:[1,0]
	v_pk_add_f32 v[0:1], v[0:1], 0 op_sel_hi:[1,0]
	s_waitcnt lgkmcnt(1)
	v_pk_add_f32 v[16:17], v[2:3], v[10:11]
	v_pk_add_f32 v[18:19], v[0:1], v[8:9]
	ds_read_b128 v[0:3], v80 offset:32768
	v_pk_add_f32 v[6:7], v[6:7], 0 op_sel_hi:[1,0]
	v_pk_add_f32 v[4:5], v[4:5], 0 op_sel_hi:[1,0]
	s_waitcnt lgkmcnt(1)
	v_pk_add_f32 v[14:15], v[6:7], v[14:15]
	v_pk_add_f32 v[12:13], v[4:5], v[12:13]
	ds_read_b128 v[4:7], v81 offset:32768
	ds_read_b128 v[8:11], v80 offset:49152
	s_waitcnt lgkmcnt(2)
	v_pk_add_f32 v[16:17], v[16:17], v[2:3]
	v_pk_add_f32 v[18:19], v[18:19], v[0:1]
	ds_read_b128 v[0:3], v81 offset:49152
	s_waitcnt lgkmcnt(2)
	v_pk_add_f32 v[14:15], v[14:15], v[6:7]
	v_pk_add_f32 v[12:13], v[12:13], v[4:5]
	ds_read_b128 v[4:7], v82
	s_waitcnt lgkmcnt(2)
	v_pk_add_f32 v[16:17], v[16:17], v[10:11]
	v_pk_add_f32 v[18:19], v[18:19], v[8:9]
	s_waitcnt lgkmcnt(1)
	v_pk_add_f32 v[14:15], v[14:15], v[2:3]
	ds_read_b128 v[8:11], v83
	v_pk_add_f32 v[12:13], v[12:13], v[0:1]
	ds_read_b128 v[0:3], v84
	s_waitcnt lgkmcnt(2)
	v_pk_add_f32 v[16:17], v[16:17], v[6:7]
	v_pk_add_f32 v[24:25], v[18:19], v[4:5]
	ds_read_b128 v[4:7], v85
	s_waitcnt lgkmcnt(2)
	v_pk_add_f32 v[26:27], v[14:15], v[10:11]
	v_pk_add_f32 v[28:29], v[12:13], v[8:9]
	s_waitcnt lgkmcnt(1)
	v_pk_add_f32 v[2:3], v[16:17], v[2:3]
	ds_read_b128 v[8:11], v86
	ds_read_b128 v[12:15], v87
	ds_read_b128 v[16:19], v88
	ds_read_b128 v[20:23], v89
	s_waitcnt lgkmcnt(4)
	v_pk_add_f32 v[4:5], v[28:29], v[4:5]
	v_pk_add_f32 v[0:1], v[24:25], v[0:1]
	s_waitcnt lgkmcnt(2)
	v_pk_add_f32 v[4:5], v[4:5], v[12:13]
	v_pk_add_f32 v[0:1], v[0:1], v[8:9]
	s_waitcnt lgkmcnt(0)
	v_pk_add_f32 v[4:5], v[4:5], v[20:21]
	v_pk_add_f32 v[0:1], v[0:1], v[16:17]
	v_mul_f32_e32 v4, 0xbfb8aa3b, v4
	v_mul_f32_e32 v5, 0xbfb8aa3b, v5
	v_exp_f32_e32 v4, v4
	v_exp_f32_e32 v5, v5
	v_pk_add_f32 v[2:3], v[2:3], v[10:11]
	v_pk_add_f32 v[6:7], v[26:27], v[6:7]
	v_pk_add_f32 v[2:3], v[2:3], v[18:19]
	v_pk_add_f32 v[4:5], v[4:5], 1.0 op_sel_hi:[1,0]
	v_pk_add_f32 v[6:7], v[6:7], v[14:15]
	v_div_scale_f32 v8, s[8:9], v5, v5, v1
	v_rcp_f32_e32 v9, v8
	v_pk_add_f32 v[6:7], v[6:7], v[22:23]
	v_fma_f32 v10, -v8, v9, 1.0
	v_fmac_f32_e32 v9, v10, v9
	v_div_scale_f32 v10, vcc, v1, v5, v1
	v_mul_f32_e32 v11, v10, v9
	v_fma_f32 v12, -v8, v11, v10
	v_fmac_f32_e32 v11, v12, v9
	v_fma_f32 v8, -v8, v11, v10
	v_div_scale_f32 v10, s[8:9], v4, v4, v0
	v_rcp_f32_e32 v12, v10
	v_mul_f32_e32 v6, 0xbfb8aa3b, v6
	v_mul_f32_e32 v7, 0xbfb8aa3b, v7
	v_div_fmas_f32 v8, v8, v9, v11
	v_exp_f32_e32 v6, v6
	v_exp_f32_e32 v7, v7
	v_div_fixup_f32 v1, v8, v5, v1
	v_fma_f32 v5, -v10, v12, 1.0
	v_fmac_f32_e32 v12, v5, v12
	v_div_scale_f32 v5, vcc, v0, v4, v0
	v_mul_f32_e32 v8, v5, v12
	v_fma_f32 v9, -v10, v8, v5
	v_pk_add_f32 v[6:7], v[6:7], 1.0 op_sel_hi:[1,0]
	v_fmac_f32_e32 v8, v9, v12
	v_div_scale_f32 v9, s[8:9], v7, v7, v3
	v_fma_f32 v5, -v10, v8, v5
	v_rcp_f32_e32 v10, v9
	v_div_fmas_f32 v5, v5, v12, v8
	v_div_fixup_f32 v0, v5, v4, v0
	v_cvt_pk_bf16_f32 v0, v0, v1
	v_fma_f32 v4, -v9, v10, 1.0
	v_fmac_f32_e32 v10, v4, v10
	v_div_scale_f32 v4, vcc, v3, v7, v3
	v_mul_f32_e32 v5, v4, v10
	v_fma_f32 v8, -v9, v5, v4
	v_fmac_f32_e32 v5, v8, v10
	v_div_scale_f32 v8, s[8:9], v6, v6, v2
	v_fma_f32 v4, -v9, v5, v4
	v_rcp_f32_e32 v9, v8
	v_div_fmas_f32 v4, v4, v10, v5
	v_div_fixup_f32 v3, v4, v7, v3
	v_fma_f32 v4, -v8, v9, 1.0
	v_fmac_f32_e32 v9, v4, v9
	v_div_scale_f32 v4, vcc, v2, v6, v2
	v_mul_f32_e32 v5, v4, v9
	v_fma_f32 v7, -v8, v5, v4
	v_fmac_f32_e32 v5, v7, v9
	v_fma_f32 v4, -v8, v5, v4
	v_div_fmas_f32 v4, v4, v9, v5
	v_div_fixup_f32 v2, v4, v6, v2
	v_cvt_pk_bf16_f32 v1, v2, v3
	v_or_b32_e32 v2, s15, v78
	v_lshlrev_b32_e32 v64, 11, v2
	v_lshl_add_u64 v[2:3], s[46:47], 0, v[64:65]
	v_lshl_or_b32 v64, s14, 6, v95
	v_lshl_add_u64 v[2:3], v[2:3], 0, v[64:65]
	v_lshl_add_u64 v[2:3], v[2:3], 0, v[70:71]
	global_store_dwordx2 v[2:3], v[0:1], off
	s_branch .LBB0_1095

.LBB0_1125:
	s_lshl_b64 s[8:9], s[8:9], 1
	v_lshl_add_u64 v[108:109], v[72:73], 0, s[8:9]
	v_add_co_u32_e32 v124, vcc, s12, v108
	v_lshl_add_u64 v[110:111], v[74:75], 0, s[8:9]
	s_nop 0
	v_addc_co_u32_e32 v125, vcc, 0, v109, vcc
	v_add_co_u32_e32 v134, vcc, s10, v108
	global_load_dwordx4 v[96:99], v[110:111], off
	s_nop 0
	v_addc_co_u32_e32 v135, vcc, 0, v109, vcc
	v_add_co_u32_e32 v144, vcc, s11, v108
	global_load_dwordx4 v[92:95], v[108:109], off
	s_nop 0
	v_addc_co_u32_e32 v145, vcc, 0, v109, vcc
	v_add_co_u32_e32 v152, vcc, s12, v110
	s_mov_b64 s[8:9], 64
	s_nop 0
	v_addc_co_u32_e32 v153, vcc, 0, v111, vcc
	v_add_co_u32_e32 v154, vcc, s10, v110
	s_nop 1
	v_addc_co_u32_e32 v155, vcc, 0, v111, vcc
	v_add_co_u32_e32 v156, vcc, s11, v110
	s_nop 1
	v_addc_co_u32_e32 v157, vcc, 0, v111, vcc
	global_load_dwordx4 v[100:103], v[108:109], off offset:64
	global_load_dwordx4 v[104:107], v[110:111], off offset:64
	s_nop 0
	global_load_dwordx4 v[108:111], v[124:125], off
	global_load_dwordx4 v[112:115], v[134:135], off
	global_load_dwordx4 v[116:119], v[144:145], off
	global_load_dwordx4 v[120:123], v[152:153], off
	s_nop 0
	global_load_dwordx4 v[124:127], v[124:125], off offset:64
	global_load_dwordx4 v[130:133], v[154:155], off
	s_nop 0
	global_load_dwordx4 v[134:137], v[134:135], off offset:64
	s_nop 0
	global_load_dwordx4 v[138:141], v[156:157], off
	global_load_dwordx4 v[148:151], v[144:145], off offset:64
	s_andn2_b64 vcc, exec, s[6:7]
	global_load_dwordx4 v[156:159], v[156:157], off offset:64
	s_mov_b64 s[6:7], 0
	global_load_dwordx4 v[160:163], v[152:153], off offset:64
	s_nop 0
	global_load_dwordx4 v[152:155], v[154:155], off offset:64
	s_waitcnt vmcnt(14)
	v_mfma_f32_16x16x32_bf16 v[8:11], v[96:99], v[92:95], v[8:11]
	s_waitcnt vmcnt(11)
	v_mfma_f32_16x16x32_bf16 v[24:27], v[96:99], v[108:111], v[24:27]
	s_waitcnt vmcnt(10)
	v_mfma_f32_16x16x32_bf16 v[36:39], v[96:99], v[112:115], v[36:39]
	s_waitcnt vmcnt(9)
	v_mfma_f32_16x16x32_bf16 v[48:51], v[96:99], v[116:119], v[48:51]
	s_waitcnt vmcnt(8)
	v_mfma_f32_16x16x32_bf16 v[0:3], v[120:123], v[92:95], v[0:3]
	s_waitcnt vmcnt(6)
	v_mfma_f32_16x16x32_bf16 v[4:7], v[130:133], v[92:95], v[4:7]
	s_waitcnt vmcnt(4)
	v_mfma_f32_16x16x32_bf16 v[12:15], v[138:141], v[92:95], v[12:15]
	v_mfma_f32_16x16x32_bf16 v[16:19], v[120:123], v[108:111], v[16:19]
	v_mfma_f32_16x16x32_bf16 v[20:23], v[130:133], v[108:111], v[20:23]
	v_mfma_f32_16x16x32_bf16 v[28:31], v[138:141], v[108:111], v[28:31]
	v_mfma_f32_16x16x32_bf16 v[32:35], v[120:123], v[112:115], v[32:35]
	v_mfma_f32_16x16x32_bf16 v[40:43], v[130:133], v[112:115], v[40:43]
	v_mfma_f32_16x16x32_bf16 v[44:47], v[138:141], v[112:115], v[44:47]
	v_mfma_f32_16x16x32_bf16 v[52:55], v[120:123], v[116:119], v[52:55]
	v_mfma_f32_16x16x32_bf16 v[56:59], v[130:133], v[116:119], v[56:59]
	v_mfma_f32_16x16x32_bf16 v[60:63], v[138:141], v[116:119], v[60:63]
	v_mfma_f32_16x16x32_bf16 v[8:11], v[104:107], v[100:103], v[8:11]
	v_mfma_f32_16x16x32_bf16 v[24:27], v[104:107], v[124:127], v[24:27]
	v_mfma_f32_16x16x32_bf16 v[36:39], v[104:107], v[134:137], v[36:39]
	s_waitcnt vmcnt(3)
	v_mfma_f32_16x16x32_bf16 v[48:51], v[104:107], v[148:151], v[48:51]
	s_waitcnt vmcnt(1)
	v_mfma_f32_16x16x32_bf16 v[0:3], v[160:163], v[100:103], v[0:3]
	s_waitcnt vmcnt(0)
	v_mfma_f32_16x16x32_bf16 v[4:7], v[152:155], v[100:103], v[4:7]
	v_mfma_f32_16x16x32_bf16 v[12:15], v[156:159], v[100:103], v[12:15]
	v_mfma_f32_16x16x32_bf16 v[16:19], v[160:163], v[124:127], v[16:19]
	v_mfma_f32_16x16x32_bf16 v[20:23], v[152:155], v[124:127], v[20:23]
	v_mfma_f32_16x16x32_bf16 v[28:31], v[156:159], v[124:127], v[28:31]
	v_mfma_f32_16x16x32_bf16 v[32:35], v[160:163], v[134:137], v[32:35]
	v_mfma_f32_16x16x32_bf16 v[40:43], v[152:155], v[134:137], v[40:43]
	v_mfma_f32_16x16x32_bf16 v[44:47], v[156:159], v[134:137], v[44:47]
	v_mfma_f32_16x16x32_bf16 v[52:55], v[160:163], v[148:151], v[52:55]
	v_mfma_f32_16x16x32_bf16 v[56:59], v[152:155], v[148:151], v[56:59]
	v_mfma_f32_16x16x32_bf16 v[60:63], v[156:159], v[148:151], v[60:63]
	s_cbranch_vccz .LBB0_1125
	s_waitcnt lgkmcnt(0)
	s_barrier
	ds_write_b128 v87, v[8:11]
	ds_write_b128 v88, v[0:3]
	ds_write_b128 v89, v[4:7]
	ds_write_b128 v90, v[12:15]
	ds_write_b128 v87, v[24:27] offset:4096
	ds_write_b128 v88, v[16:19] offset:4096
	ds_write_b128 v89, v[20:23] offset:4096
	ds_write_b128 v90, v[28:31] offset:4096
	ds_write_b128 v87, v[36:39] offset:8192
	ds_write_b128 v88, v[32:35] offset:8192
	ds_write_b128 v89, v[40:43] offset:8192
	ds_write_b128 v90, v[44:47] offset:8192
	ds_write_b128 v87, v[48:51] offset:12288
	ds_write_b128 v88, v[52:55] offset:12288
	ds_write_b128 v89, v[56:59] offset:12288
	ds_write_b128 v90, v[60:63] offset:12288
	s_waitcnt lgkmcnt(0)
	s_barrier
	s_and_saveexec_b64 s[6:7], s[4:5]
	s_cbranch_execz .LBB0_1123
	ds_read_b128 v[0:3], v76
	ds_read_b128 v[4:7], v77
	ds_read_b128 v[8:11], v76 offset:16384
	ds_read_b128 v[12:15], v77 offset:16384
	v_mov_b32_e32 v71, v65
	s_waitcnt lgkmcnt(3)
	v_pk_add_f32 v[2:3], v[2:3], 0 op_sel_hi:[1,0]
	v_pk_add_f32 v[0:1], v[0:1], 0 op_sel_hi:[1,0]
	s_waitcnt lgkmcnt(1)
	v_pk_add_f32 v[16:17], v[2:3], v[10:11]
	v_pk_add_f32 v[18:19], v[0:1], v[8:9]
	ds_read_b128 v[0:3], v76 offset:32768
	v_pk_add_f32 v[6:7], v[6:7], 0 op_sel_hi:[1,0]
	v_pk_add_f32 v[4:5], v[4:5], 0 op_sel_hi:[1,0]
	s_waitcnt lgkmcnt(1)
	v_pk_add_f32 v[14:15], v[6:7], v[14:15]
	v_pk_add_f32 v[12:13], v[4:5], v[12:13]
	ds_read_b128 v[4:7], v77 offset:32768
	ds_read_b128 v[8:11], v76 offset:49152
	s_waitcnt lgkmcnt(2)
	v_pk_add_f32 v[16:17], v[16:17], v[2:3]
	v_pk_add_f32 v[18:19], v[18:19], v[0:1]
	ds_read_b128 v[0:3], v77 offset:49152
	s_waitcnt lgkmcnt(2)
	v_pk_add_f32 v[14:15], v[14:15], v[6:7]
	v_pk_add_f32 v[12:13], v[12:13], v[4:5]
	ds_read_b128 v[4:7], v78
	s_waitcnt lgkmcnt(2)
	v_pk_add_f32 v[16:17], v[16:17], v[10:11]
	v_pk_add_f32 v[18:19], v[18:19], v[8:9]
	s_waitcnt lgkmcnt(1)
	v_pk_add_f32 v[14:15], v[14:15], v[2:3]
	ds_read_b128 v[8:11], v79
	v_pk_add_f32 v[12:13], v[12:13], v[0:1]
	ds_read_b128 v[0:3], v80
	s_waitcnt lgkmcnt(2)
	v_pk_add_f32 v[16:17], v[16:17], v[6:7]
	v_pk_add_f32 v[24:25], v[18:19], v[4:5]
	ds_read_b128 v[4:7], v81
	s_waitcnt lgkmcnt(2)
	v_pk_add_f32 v[26:27], v[14:15], v[10:11]
	v_pk_add_f32 v[28:29], v[12:13], v[8:9]
	s_waitcnt lgkmcnt(1)
	v_pk_add_f32 v[2:3], v[16:17], v[2:3]
	ds_read_b128 v[8:11], v82
	ds_read_b128 v[12:15], v83
	ds_read_b128 v[16:19], v84
	ds_read_b128 v[20:23], v85
	s_waitcnt lgkmcnt(4)
	v_pk_add_f32 v[4:5], v[28:29], v[4:5]
	v_pk_add_f32 v[0:1], v[24:25], v[0:1]
	s_waitcnt lgkmcnt(2)
	v_pk_add_f32 v[4:5], v[4:5], v[12:13]
	v_pk_add_f32 v[0:1], v[0:1], v[8:9]
	s_waitcnt lgkmcnt(0)
	v_pk_add_f32 v[4:5], v[4:5], v[20:21]
	v_pk_add_f32 v[0:1], v[0:1], v[16:17]
	v_mul_f32_e32 v4, 0xbfb8aa3b, v4
	v_mul_f32_e32 v5, 0xbfb8aa3b, v5
	v_exp_f32_e32 v4, v4
	v_exp_f32_e32 v5, v5
	v_pk_add_f32 v[2:3], v[2:3], v[10:11]
	v_pk_add_f32 v[6:7], v[26:27], v[6:7]
	v_pk_add_f32 v[2:3], v[2:3], v[18:19]
	v_pk_add_f32 v[4:5], v[4:5], 1.0 op_sel_hi:[1,0]
	v_pk_add_f32 v[6:7], v[6:7], v[14:15]
	v_div_scale_f32 v8, s[8:9], v5, v5, v1
	v_rcp_f32_e32 v9, v8
	v_pk_add_f32 v[6:7], v[6:7], v[22:23]
	v_fma_f32 v10, -v8, v9, 1.0
	v_fmac_f32_e32 v9, v10, v9
	v_div_scale_f32 v10, vcc, v1, v5, v1
	v_mul_f32_e32 v11, v10, v9
	v_fma_f32 v12, -v8, v11, v10
	v_fmac_f32_e32 v11, v12, v9
	v_fma_f32 v8, -v8, v11, v10
	v_div_scale_f32 v10, s[8:9], v4, v4, v0
	v_rcp_f32_e32 v12, v10
	v_mul_f32_e32 v6, 0xbfb8aa3b, v6
	v_mul_f32_e32 v7, 0xbfb8aa3b, v7
	v_div_fmas_f32 v8, v8, v9, v11
	v_exp_f32_e32 v6, v6
	v_exp_f32_e32 v7, v7
	v_div_fixup_f32 v1, v8, v5, v1
	v_fma_f32 v5, -v10, v12, 1.0
	v_fmac_f32_e32 v12, v5, v12
	v_div_scale_f32 v5, vcc, v0, v4, v0
	v_mul_f32_e32 v8, v5, v12
	v_fma_f32 v9, -v10, v8, v5
	v_pk_add_f32 v[6:7], v[6:7], 1.0 op_sel_hi:[1,0]
	v_fmac_f32_e32 v8, v9, v12
	v_div_scale_f32 v9, s[8:9], v7, v7, v3
	v_fma_f32 v5, -v10, v8, v5
	v_rcp_f32_e32 v10, v9
	v_div_fmas_f32 v5, v5, v12, v8
	v_div_fixup_f32 v0, v5, v4, v0
	v_cvt_pk_bf16_f32 v0, v0, v1
	v_fma_f32 v4, -v9, v10, 1.0
	v_fmac_f32_e32 v10, v4, v10
	v_div_scale_f32 v4, vcc, v3, v7, v3
	v_mul_f32_e32 v5, v4, v10
	v_fma_f32 v8, -v9, v5, v4
	v_fmac_f32_e32 v5, v8, v10
	v_div_scale_f32 v8, s[8:9], v6, v6, v2
	v_fma_f32 v4, -v9, v5, v4
	v_rcp_f32_e32 v9, v8
	v_div_fmas_f32 v4, v4, v10, v5
	v_div_fixup_f32 v3, v4, v7, v3
	v_fma_f32 v4, -v8, v9, 1.0
	v_fmac_f32_e32 v9, v4, v9
	v_div_scale_f32 v4, vcc, v2, v6, v2
	v_mul_f32_e32 v5, v4, v9
	v_fma_f32 v7, -v8, v5, v4
	v_fmac_f32_e32 v5, v7, v9
	v_fma_f32 v4, -v8, v5, v4
	v_div_fmas_f32 v4, v4, v9, v5
	v_div_fixup_f32 v2, v4, v6, v2
	v_cvt_pk_bf16_f32 v1, v2, v3
	v_or_b32_e32 v2, s15, v142
	v_lshlrev_b32_e32 v64, 11, v2
	v_lshl_add_u64 v[2:3], s[46:47], 0, v[64:65]
	v_lshl_or_b32 v64, s14, 6, v91
	v_lshl_add_u64 v[2:3], v[2:3], 0, v[64:65]
	v_lshl_add_u64 v[2:3], v[2:3], 0, v[70:71]
	global_store_dwordx2 v[2:3], v[0:1], off
	s_branch .LBB0_1123

.LBB0_1268:
	s_lshl_b64 s[10:11], s[10:11], 1
	v_lshl_add_u64 v[108:109], v[70:71], 0, s[10:11]
	v_add_co_u32_e32 v116, vcc, s16, v108
	v_lshl_add_u64 v[110:111], v[72:73], 0, s[10:11]
	s_nop 0
	v_addc_co_u32_e32 v117, vcc, 0, v109, vcc
	v_add_co_u32_e32 v124, vcc, s17, v108
	global_load_dwordx4 v[88:91], v[110:111], off
	s_nop 0
	v_addc_co_u32_e32 v125, vcc, 0, v109, vcc
	v_add_co_u32_e32 v134, vcc, s18, v108
	global_load_dwordx4 v[84:87], v[108:109], off
	s_nop 0
	v_addc_co_u32_e32 v135, vcc, 0, v109, vcc
	v_add_co_u32_e32 v138, vcc, s16, v110
	s_mov_b64 s[10:11], 64
	s_nop 0
	v_addc_co_u32_e32 v139, vcc, 0, v111, vcc
	v_add_co_u32_e32 v140, vcc, s17, v110
	s_nop 1
	v_addc_co_u32_e32 v141, vcc, 0, v111, vcc
	v_add_co_u32_e32 v142, vcc, s18, v110
	s_nop 1
	v_addc_co_u32_e32 v143, vcc, 0, v111, vcc
	global_load_dwordx4 v[92:95], v[108:109], off offset:64
	global_load_dwordx4 v[96:99], v[110:111], off offset:64
	global_load_dwordx4 v[100:103], v[116:117], off
	global_load_dwordx4 v[104:107], v[124:125], off
	s_nop 0
	global_load_dwordx4 v[108:111], v[134:135], off
	global_load_dwordx4 v[112:115], v[138:139], off
	s_nop 0
	global_load_dwordx4 v[116:119], v[116:117], off offset:64
	global_load_dwordx4 v[120:123], v[140:141], off
	s_nop 0
	global_load_dwordx4 v[124:127], v[124:125], off offset:64
	s_nop 0
	global_load_dwordx4 v[130:133], v[142:143], off
	s_nop 0
	global_load_dwordx4 v[134:137], v[134:135], off offset:64
	s_andn2_b64 vcc, exec, s[8:9]
	global_load_dwordx4 v[142:145], v[142:143], off offset:64
	s_mov_b64 s[8:9], 0
	global_load_dwordx4 v[160:163], v[138:139], off offset:64
	s_nop 0
	global_load_dwordx4 v[138:141], v[140:141], off offset:64
	s_waitcnt vmcnt(14)
	v_mfma_f32_16x16x32_bf16 v[8:11], v[88:91], v[84:87], v[8:11]
	s_waitcnt vmcnt(11)
	v_mfma_f32_16x16x32_bf16 v[24:27], v[88:91], v[100:103], v[24:27]
	s_waitcnt vmcnt(10)
	v_mfma_f32_16x16x32_bf16 v[36:39], v[88:91], v[104:107], v[36:39]
	s_waitcnt vmcnt(9)
	v_mfma_f32_16x16x32_bf16 v[48:51], v[88:91], v[108:111], v[48:51]
	s_waitcnt vmcnt(8)
	v_mfma_f32_16x16x32_bf16 v[0:3], v[112:115], v[84:87], v[0:3]
	s_waitcnt vmcnt(6)
	v_mfma_f32_16x16x32_bf16 v[4:7], v[120:123], v[84:87], v[4:7]
	s_waitcnt vmcnt(4)
	v_mfma_f32_16x16x32_bf16 v[12:15], v[130:133], v[84:87], v[12:15]
	v_mfma_f32_16x16x32_bf16 v[16:19], v[112:115], v[100:103], v[16:19]
	v_mfma_f32_16x16x32_bf16 v[20:23], v[120:123], v[100:103], v[20:23]
	v_mfma_f32_16x16x32_bf16 v[28:31], v[130:133], v[100:103], v[28:31]
	v_mfma_f32_16x16x32_bf16 v[32:35], v[112:115], v[104:107], v[32:35]
	v_mfma_f32_16x16x32_bf16 v[40:43], v[120:123], v[104:107], v[40:43]
	v_mfma_f32_16x16x32_bf16 v[44:47], v[130:133], v[104:107], v[44:47]
	v_mfma_f32_16x16x32_bf16 v[52:55], v[112:115], v[108:111], v[52:55]
	v_mfma_f32_16x16x32_bf16 v[56:59], v[120:123], v[108:111], v[56:59]
	v_mfma_f32_16x16x32_bf16 v[60:63], v[130:133], v[108:111], v[60:63]
	v_mfma_f32_16x16x32_bf16 v[8:11], v[96:99], v[92:95], v[8:11]
	v_mfma_f32_16x16x32_bf16 v[24:27], v[96:99], v[116:119], v[24:27]
	v_mfma_f32_16x16x32_bf16 v[36:39], v[96:99], v[124:127], v[36:39]
	s_waitcnt vmcnt(3)
	v_mfma_f32_16x16x32_bf16 v[48:51], v[96:99], v[134:137], v[48:51]
	s_waitcnt vmcnt(1)
	v_mfma_f32_16x16x32_bf16 v[0:3], v[160:163], v[92:95], v[0:3]
	s_waitcnt vmcnt(0)
	v_mfma_f32_16x16x32_bf16 v[4:7], v[138:141], v[92:95], v[4:7]
	v_mfma_f32_16x16x32_bf16 v[12:15], v[142:145], v[92:95], v[12:15]
	v_mfma_f32_16x16x32_bf16 v[16:19], v[160:163], v[116:119], v[16:19]
	v_mfma_f32_16x16x32_bf16 v[20:23], v[138:141], v[116:119], v[20:23]
	v_mfma_f32_16x16x32_bf16 v[28:31], v[142:145], v[116:119], v[28:31]
	v_mfma_f32_16x16x32_bf16 v[32:35], v[160:163], v[124:127], v[32:35]
	v_mfma_f32_16x16x32_bf16 v[40:43], v[138:141], v[124:127], v[40:43]
	v_mfma_f32_16x16x32_bf16 v[44:47], v[142:145], v[124:127], v[44:47]
	v_mfma_f32_16x16x32_bf16 v[52:55], v[160:163], v[134:137], v[52:55]
	v_mfma_f32_16x16x32_bf16 v[56:59], v[138:141], v[134:137], v[56:59]
	v_mfma_f32_16x16x32_bf16 v[60:63], v[142:145], v[134:137], v[60:63]
	s_cbranch_vccz .LBB0_1268
	s_lshl_b32 s8, s12, 12
	s_and_b32 s8, s8, 0x1c0000
	s_and_b32 s9, s14, 0xfc0
	s_or_b32 s8, s9, s8
	v_add_lshl_u32 v64, s8, v76, 1
	v_lshl_add_u64 v[70:71], s[46:47], 0, v[64:65]
	s_barrier
	ds_write_b128 v80, v[8:11]
	ds_write_b128 v81, v[0:3]
	ds_write_b128 v82, v[4:7]
	ds_write_b128 v83, v[12:15]
	ds_write_b128 v80, v[24:27] offset:4096
	ds_write_b128 v81, v[16:19] offset:4096
	ds_write_b128 v82, v[20:23] offset:4096
	ds_write_b128 v83, v[28:31] offset:4096
	ds_write_b128 v80, v[36:39] offset:8192
	ds_write_b128 v81, v[32:35] offset:8192
	ds_write_b128 v82, v[40:43] offset:8192
	ds_write_b128 v83, v[44:47] offset:8192
	ds_write_b128 v80, v[48:51] offset:12288
	ds_write_b128 v81, v[52:55] offset:12288
	ds_write_b128 v82, v[56:59] offset:12288
	ds_write_b128 v83, v[60:63] offset:12288
	s_mov_b64 s[8:9], 0
	v_mov_b32_e32 v0, v78
	v_mov_b32_e32 v1, v77
	v_mov_b32_e32 v2, v75
	s_waitcnt lgkmcnt(0)
	s_barrier
